# team barriers now also wait for the teams whose rows overlap the byte range rewritten in a new row pitch (fixes a cross-team write-after-read race on the shared activation buffer); K-loop cleanup
# speedup vs baseline: 1.0007x; 1.0007x over previous
.Ltb_go:
	v_readlane_b32 s1, v243, 19
	s_mov_b32 s34, 0
	s_cmp_eq_u32 s1, 2
	s_cselect_b32 s34, 9, s34
	s_cselect_b32 s35, 5958, s35
	s_cmp_eq_u32 s1, 5
	s_cselect_b32 s34, 4, s34
	s_cselect_b32 s35, 7282, s35
	s_cmp_eq_u32 s1, 8
	s_cselect_b32 s34, 11, s34
	s_cselect_b32 s35, 16384, s35
	s_cmp_eq_u32 s1, 12
	s_cselect_b32 s34, 12, s34
	s_cselect_b32 s35, 5958, s35
	s_cmp_eq_u32 s1, 15
	s_cselect_b32 s34, 4, s34
	s_cselect_b32 s35, 5462, s35
	s_cmp_eq_u32 s1, 18
	s_cselect_b32 s34, 11, s34
	s_cselect_b32 s35, 16384, s35
	s_cmp_eq_u32 s34, 0
	s_cbranch_scc1 .LBB0_7
	v_readlane_b32 s1, v243, 16
	s_and_b32 s28, s1, 7
	s_lshl_b32 s28, s28, 3
	s_bfe_u32 s29, s1, 0x30003
	s_add_i32 s28, s28, s29
	s_mul_i32 s29, s28, s34
	s_add_i32 s1, s29, s34
	s_add_i32 s1, s1, -1
	s_mul_i32 s29, s29, s35
	s_lshr_b32 s28, s29, 16
	s_mul_i32 s1, s1, s35
	s_lshr_b32 s1, s1, 16
	s_min_u32 s1, s1, 63
.Ltb_nb_loop:
	s_cmp_gt_u32 s28, s1
	s_cbranch_scc1 .LBB0_7
	s_lshr_b32 s29, s28, 3
	s_and_b32 vcc_lo, s28, 7
	s_lshl_b32 vcc_lo, vcc_lo, 3
	s_add_i32 s29, s29, vcc_lo
	s_lshl_b32 s29, s29, 5
	s_add_u32 s34, s96, 0xeb12d00
	s_addc_u32 s35, s97, 0
	s_add_u32 s34, s34, s29
	s_addc_u32 s35, s35, 0
.Ltb_nb_poll:
	global_load_dword v2, v0, s[34:35] sc1
	s_waitcnt vmcnt(0)
	v_readfirstlane_b32 s29, v2
	s_cmp_ge_u32 s29, s0
	s_cbranch_scc1 .Ltb_nb_next
	s_sleep 1
	s_branch .Ltb_nb_poll
.Ltb_nb_next:
	s_add_i32 s28, s28, 1
	s_branch .Ltb_nb_loop
	s_branch .LBB0_7
